# v72 plus attention local tiles: the +16 of the 32 bias-table LDS addresses folded into the ds_read immediate offset (32 v_add per tile removed)
# baseline (speedup 1.0000x reference)
.LBB0_295:
	s_andn2_saveexec_b64 s[36:37], s[36:37]
	s_cbranch_execz .LBB0_263
	v_add_u32_e32 v4, s54, v120
	v_cmp_ge_u32_e32 vcc, v4, v122
	v_cmp_le_u32_e64 s[44:45], v4, v130
	s_and_b64 s[50:51], vcc, s[44:45]
	s_and_saveexec_b64 s[44:45], s[50:51]
	s_cbranch_execz .LBB0_262
	v_add_u32_e32 v185, s53, v163
	v_add_u32_e32 v4, v185, v8
	ds_read_b128 v[64:67], v4
	ds_read_b128 v[68:71], v4 offset:4096
	v_add_u32_e32 v4, v185, v7
	ds_read_b128 v[96:99], v4
	ds_read_b128 v[104:107], v4 offset:4096
	v_add_u32_e32 v4, v185, v6
	v_add_u32_e32 v0, v185, v0
	ds_read_b128 v[12:15], v4
	ds_read_b128 v[100:103], v4 offset:4096
	ds_read_b128 v[4:7], v0
	ds_read_b128 v[8:11], v0 offset:4096
	s_and_saveexec_b64 s[50:51], s[42:43]
	s_xor_b64 s[50:51], exec, s[50:51]
	s_cbranch_execz .LBB0_301
	s_waitcnt lgkmcnt(0)
	v_mfma_f32_32x32x16_f16 v[48:63], v[68:71], v[88:91], 0
	v_mfma_f32_32x32x16_f16 v[48:63], v[104:107], v[80:83], v[48:63]
	v_mfma_f32_32x32x16_f16 v[48:63], v[100:103], v[84:87], v[48:63]
	v_mfma_f32_32x32x16_f16 v[48:63], v[8:11], v[92:95], v[48:63]
	ds_read_b32 v8, v149 offset:16
	ds_read_b32 v9, v147 offset:16
	ds_read_b32 v11, v145 offset:16
	ds_read_b32 v72, v143 offset:16
	ds_read_b32 v102, v154 offset:16
	ds_read_b32 v103, v153 offset:16
	ds_read_b32 v104, v152 offset:16
	ds_read_b32 v105, v151 offset:16
	s_waitcnt lgkmcnt(0)
	s_nop 2
	v_add_f32_e32 v100, v48, v8
	v_add_f32_e32 v8, v51, v72
	v_mfma_f32_32x32x16_f16 v[64:79], v[64:67], v[88:91], 0
	v_add_f32_e32 v10, v49, v9
	v_add_f32_e32 v9, v50, v11
	v_mfma_f32_32x32x16_f16 v[64:79], v[96:99], v[80:83], v[64:79]
	ds_read_b32 v96, v162 offset:16
	ds_read_b32 v11, v161 offset:16
	ds_read_b32 v48, v160 offset:16
	ds_read_b32 v49, v159 offset:16
	ds_read_b32 v50, v158 offset:16
	ds_read_b32 v98, v157 offset:16
	ds_read_b32 v99, v156 offset:16
	ds_read_b32 v101, v155 offset:16
	s_waitcnt lgkmcnt(0)
	v_add_f32_e32 v97, v52, v96
	v_add_f32_e32 v96, v53, v11
	v_add_f32_e32 v53, v54, v48
	v_add_f32_e32 v52, v55, v49
	v_add_f32_e32 v51, v56, v50
	v_add_f32_e32 v50, v57, v98
	v_mfma_f32_32x32x16_f16 v[64:79], v[12:15], v[84:87], v[64:79]
	ds_read_b32 v11, v134 offset:16
	ds_read_b32 v12, v133 offset:16
	ds_read_b32 v48, v132 offset:16
	ds_read_b32 v0, v131 offset:16
	v_add_f32_e32 v15, v58, v99
	v_add_f32_e32 v14, v59, v101
	v_add_f32_e32 v13, v60, v102
	v_mfma_f32_32x32x16_f16 v[64:79], v[4:7], v[92:95], v[64:79]
	v_add_f32_e32 v6, v62, v104
	v_add_f32_e32 v4, v63, v105
	s_waitcnt lgkmcnt(0)
	s_nop 8
	v_add_f32_e32 v5, v79, v0
	v_max3_f32 v0, v100, s55, v10
	v_max3_f32 v0, v0, v9, v8
	v_max3_f32 v0, v0, v97, v96
	v_max3_f32 v0, v0, v53, v52
	v_max3_f32 v0, v0, v51, v50
	v_add_f32_e32 v49, v76, v11
	v_max3_f32 v0, v0, v15, v14
	v_add_f32_e32 v12, v77, v12
	v_add_f32_e32 v11, v61, v103
	v_max3_f32 v0, v0, v49, v13
	v_add_f32_e32 v7, v78, v48
	v_max3_f32 v0, v0, v12, v11
	v_max3_f32 v0, v0, v7, v6
	v_max3_f32 v0, v0, v5, v4
	v_mov_b32_e32 v48, v0
	s_nop 1
	v_permlane32_swap_b32_e32 v0, v48
	v_max3_f32 v48, v186, v0, v48
	v_sub_f32_e32 v0, v186, v48
	v_exp_f32_e32 v0, v0
	s_nop 0
	v_cmp_neq_f32_e32 vcc, 1.0, v0
	s_cbranch_vccz .LBB0_300
	v_mul_f32_e32 v30, v0, v30
	v_mul_f32_e32 v31, v0, v31
	v_mul_f32_e32 v28, v0, v28
	v_mul_f32_e32 v29, v0, v29
	v_mul_f32_e32 v26, v0, v26
	v_mul_f32_e32 v27, v0, v27
	v_mul_f32_e32 v24, v0, v24
	v_mul_f32_e32 v25, v0, v25
	v_mul_f32_e32 v22, v0, v22
	v_mul_f32_e32 v23, v0, v23
	v_mul_f32_e32 v20, v0, v20
	v_mul_f32_e32 v21, v0, v21
	v_mul_f32_e32 v18, v0, v18
	v_mul_f32_e32 v19, v0, v19
	v_mul_f32_e32 v16, v0, v16
	v_mul_f32_e32 v17, v0, v17
	v_mul_f32_e32 v46, v0, v46
	v_mul_f32_e32 v47, v0, v47
	v_mul_f32_e32 v44, v0, v44
	v_mul_f32_e32 v45, v0, v45
	v_mul_f32_e32 v42, v0, v42
	v_mul_f32_e32 v43, v0, v43
	v_mul_f32_e32 v40, v0, v40
	v_mul_f32_e32 v41, v0, v41
	v_mul_f32_e32 v38, v0, v38
	v_mul_f32_e32 v39, v0, v39
	v_mul_f32_e32 v36, v0, v36
	v_mul_f32_e32 v37, v0, v37
	v_mul_f32_e32 v34, v0, v34
	v_mul_f32_e32 v35, v0, v35
	v_mul_f32_e32 v32, v0, v32
	v_mul_f32_e32 v33, v0, v33

.LBB0_301:
	s_andn2_saveexec_b64 s[50:51], s[50:51]
	s_cbranch_execz .LBB0_261
	s_waitcnt lgkmcnt(0)
	v_mfma_f32_32x32x16_f16 v[48:63], v[64:67], v[88:91], 0
	v_mfma_f32_32x32x16_f16 v[64:79], v[68:71], v[88:91], 0
	v_mfma_f32_32x32x16_f16 v[48:63], v[96:99], v[80:83], v[48:63]
	v_mfma_f32_32x32x16_f16 v[64:79], v[104:107], v[80:83], v[64:79]
	v_mfma_f32_32x32x16_f16 v[48:63], v[12:15], v[84:87], v[48:63]
	v_mfma_f32_32x32x16_f16 v[64:79], v[100:103], v[84:87], v[64:79]
	v_mfma_f32_32x32x16_f16 v[48:63], v[4:7], v[92:95], v[48:63]
	ds_read_b32 v4, v150 offset:16
	ds_read_b32 v5, v148 offset:16
	ds_read_b32 v6, v146 offset:16
	ds_read_b32 v7, v144 offset:16
	ds_read_b32 v12, v142 offset:16
	ds_read_b32 v13, v141 offset:16
	ds_read_b32 v97, v140 offset:16
	ds_read_b32 v98, v139 offset:16
	s_waitcnt lgkmcnt(0)
	s_nop 0
	v_add_f32_e32 v96, v48, v4
	v_mfma_f32_32x32x16_f16 v[64:79], v[8:11], v[92:95], v[64:79]
	ds_read_b32 v99, v149 offset:16
	ds_read_b32 v100, v147 offset:16
	ds_read_b32 v101, v145 offset:16
	ds_read_b32 v102, v143 offset:16
	ds_read_b32 v4, v138 offset:16
	ds_read_b32 v103, v137 offset:16
	ds_read_b32 v104, v136 offset:16
	ds_read_b32 v48, v135 offset:16
	s_nop 1
	v_add_f32_e32 v69, v49, v5
	s_waitcnt lgkmcnt(0)
	v_add_f32_e32 v11, v56, v4
	v_add_f32_e32 v15, v52, v12
	v_add_f32_e32 v14, v53, v13
	v_add_f32_e32 v68, v65, v100
	v_add_f32_e32 v65, v50, v6
	v_add_f32_e32 v50, v51, v7
	ds_read_b32 v4, v134 offset:16
	ds_read_b32 v5, v133 offset:16
	ds_read_b32 v51, v132 offset:16
	ds_read_b32 v0, v131 offset:16
	v_add_f32_e32 v70, v64, v99
	s_waitcnt lgkmcnt(0)
	v_add_f32_e32 v7, v60, v4
	v_add_f32_e32 v64, v66, v101
	v_add_f32_e32 v49, v67, v102
	v_add_f32_e32 v4, v63, v0
	v_max3_f32 v0, v96, s55, v70
	v_max3_f32 v0, v0, v69, v68
	v_max3_f32 v0, v0, v65, v64
	v_max3_f32 v0, v0, v50, v49
	v_add_f32_e32 v13, v54, v97
	v_add_f32_e32 v12, v55, v98
	v_max3_f32 v0, v0, v15, v14
	v_add_f32_e32 v10, v57, v103
	v_max3_f32 v0, v0, v13, v12
	v_add_f32_e32 v9, v58, v104
	v_add_f32_e32 v8, v59, v48
	v_max3_f32 v0, v0, v11, v10
	v_add_f32_e32 v6, v61, v5
	v_max3_f32 v0, v0, v9, v8
	v_add_f32_e32 v5, v62, v51
	v_max3_f32 v0, v0, v7, v6
	v_max3_f32 v0, v0, v5, v4
	v_mov_b32_e32 v48, v0
	s_nop 1
	v_permlane32_swap_b32_e32 v0, v48
	v_max3_f32 v48, v186, v0, v48
	v_sub_f32_e32 v0, v186, v48
	v_exp_f32_e32 v0, v0
	s_nop 0
	v_cmp_neq_f32_e32 vcc, 1.0, v0
	s_cbranch_vccz .LBB0_260
	v_mul_f32_e32 v30, v0, v30
	v_mul_f32_e32 v31, v0, v31
	v_mul_f32_e32 v28, v0, v28
	v_mul_f32_e32 v29, v0, v29
	v_mul_f32_e32 v26, v0, v26
	v_mul_f32_e32 v27, v0, v27
	v_mul_f32_e32 v24, v0, v24
	v_mul_f32_e32 v25, v0, v25
	v_mul_f32_e32 v22, v0, v22
	v_mul_f32_e32 v23, v0, v23
	v_mul_f32_e32 v20, v0, v20
	v_mul_f32_e32 v21, v0, v21
	v_mul_f32_e32 v18, v0, v18
	v_mul_f32_e32 v19, v0, v19
	v_mul_f32_e32 v16, v0, v16
	v_mul_f32_e32 v17, v0, v17
	v_mul_f32_e32 v46, v0, v46
	v_mul_f32_e32 v47, v0, v47
	v_mul_f32_e32 v44, v0, v44
	v_mul_f32_e32 v45, v0, v45
	v_mul_f32_e32 v42, v0, v42
	v_mul_f32_e32 v43, v0, v43
	v_mul_f32_e32 v40, v0, v40
	v_mul_f32_e32 v41, v0, v41
	v_mul_f32_e32 v38, v0, v38
	v_mul_f32_e32 v39, v0, v39
	v_mul_f32_e32 v36, v0, v36
	v_mul_f32_e32 v37, v0, v37
	v_mul_f32_e32 v34, v0, v34
	v_mul_f32_e32 v35, v0, v35
	v_mul_f32_e32 v32, v0, v32
	v_mul_f32_e32 v33, v0, v33
	s_branch .LBB0_260
